# code placement: the two hand-written attention loop heads aligned to 64 bytes (they sat at addresses = 4 mod 8)
# baseline (speedup 1.0000x reference)
; __device__ __forceinline__ void attn_unit(const Args& a, int l, int b, int h, int R0, bool special, LAS unsigned char* lds, float kb, int wv, bool pre, bool hasn, int nb, int nh, int nR0) {
;     ...
;     {
;         f32x16 pb0, pb1; int t = 1;
;         for (; t + 1 < tw; t += 2) { ATT_BODY(t, pc0, pc1, pb0, pb1); ATT_BODY(t + 1, pb0, pb1, pc0, pc1); }
.Lfa_entry:
	v_mov_b32_e32 v210, 0
	v_mov_b32_e32 v211, 0
	v_mov_b32_e32 v212, 0
	v_mov_b32_e32 v213, 0
	v_mov_b32_e32 v214, 0
	v_mov_b32_e32 v215, 0
	v_mov_b32_e32 v216, 0
	v_mov_b32_e32 v217, 0
	v_mov_b32_e32 v218, 0
	v_mov_b32_e32 v219, 0
	v_mov_b32_e32 v220, 0
	v_mov_b32_e32 v221, 0
	v_mov_b32_e32 v222, 0
	v_mov_b32_e32 v223, 0
	v_mov_b32_e32 v224, 0
	v_mov_b32_e32 v225, 0
	v_mov_b32_e32 v234, 0
	v_mov_b32_e32 v235, 0
	v_mov_b32_e32 v236, 0
	v_mov_b32_e32 v237, 0
	v_mov_b32_e32 v238, 0
	v_mov_b32_e32 v239, 0
	v_mov_b32_e32 v240, 0
	v_mov_b32_e32 v241, 0
	v_mov_b32_e32 v248, 0
	v_mov_b32_e32 v249, 0
	v_mov_b32_e32 v250, 0
	v_mov_b32_e32 v251, 0
	s_mov_b32 s0, 0xd000
	v_add3_u32 v247, v26, v28, s0
	v_readfirstlane_b32 s22, v20
	v_readfirstlane_b32 s23, v21
	s_nop 1
	v_subrev_u32_e32 v0, s22, v20
	v_subrev_u32_e32 v14, s22, v18
	s_add_u32 s22, s22, 0x220c000
	s_addc_u32 s23, s23, 0
	v_readfirstlane_b32 s34, v22
	v_readfirstlane_b32 s35, v23
	s_nop 1
	v_subrev_u32_e32 v15, s34, v22
	v_subrev_u32_e32 v197, s34, v24
	s_add_u32 s34, s34, 0x1b900180
	s_addc_u32 s35, s35, 0
	s_and_b32 s88, s87, 3
	s_mulk_i32 s88, 0x3400
	s_add_i32 s90, s87, 1
	s_and_b32 s90, s90, 3
	s_mulk_i32 s90, 0x3400
	s_mov_b32 s32, 0
	s_movk_i32 s30, 0x2400
	s_mov_b32 s31, 0
	s_add_i32 s24, s77, -1
	s_add_i32 s0, s73, -3
	s_min_i32 s24, s24, s0
	s_add_i32 s0, s74, 1
	s_ashr_i32 s0, s0, 6
	s_min_i32 s24, s24, s0
	s_add_i32 s76, s87, 2
	s_cmp_le_i32 s76, s24
	s_cbranch_scc0 .Lfa_loop
	.p2align 6

; __device__ __forceinline__ void attn_unit(const Args& a, int l, int b, int h, int R0, bool special, LAS unsigned char* lds, float kb, int wv, bool pre, bool hasn, int nb, int nh, int nR0) {
;     ...
;         for (; t + 1 < tw; t += 2) { ATT_BODY(t, pc0, pc1, pb0, pb1); ATT_BODY(t + 1, pb0, pb1, pc0, pc1); }
.Lfa_bs_wj:
	s_waitcnt lgkmcnt(0)
	s_barrier
	s_addk_i32 s83, 0x4800
	s_addk_i32 s84, 0x80
	s_addk_i32 s85, 0x4800
	s_add_i32 s79, s79, 2
	s_add_i32 s86, s86, 2
	s_add_i32 s80, s80, 2
	s_add_i32 s32, s32, 1
	s_xor_b32 s88, s88, 0x6800
	s_xor_b32 s90, s90, 0xa800
	s_mov_b32 s87, s76
	s_add_i32 s0, s76, 2
	s_cmp_le_i32 s0, s24
	s_cbranch_scc1 .Lfa_sloop
	s_cmp_lt_i32 s76, s77
	s_cbranch_scc0 .Lfa_exit
	.p2align 6
